# P4/P7 epilogues: wait for the first load batch narrowed to its first consumers
# speedup vs baseline: 1.0013x; 1.0013x over previous
.LBB0_665:
	v_mov_b32_e32 v236, v229
	v_mov_b32_e32 v237, v228
	v_mov_b32_e32 v238, v0
	s_ashr_i32 s0, s64, 3
	s_lshl_b32 s10, s64, 8
	s_lshl_b32 s55, s62, 8
	v_lshlrev_b32_e32 v239, 2, v236
	s_mul_hi_i32 s1, s0, 0x1800
	s_mulk_i32 s0, 0x1800
	s_add_i32 s31, s10, s85
	v_add_u32_e32 v130, s55, v239
	s_lshl_b64 s[66:67], s[0:1], 2
	s_add_u32 s0, s81, s66
	v_ashrrev_i32_e32 v131, 31, v130
	v_add_u32_e32 v224, s31, v237
	s_addc_u32 s1, s82, s67
	v_lshlrev_b64 v[130:131], 2, v[130:131]
	v_ashrrev_i32_e32 v225, 31, v224
	v_lshl_add_u64 v[132:133], s[0:1], 0, v[130:131]
	v_lshl_add_u64 v[226:227], s[36:37], 0, v[130:131]
	v_lshlrev_b64 v[130:131], 12, v[224:225]
	v_lshl_add_u64 v[132:133], v[132:133], 0, s[42:43]
	v_lshl_add_u64 v[130:131], v[226:227], 0, v[130:131]
	v_lshl_add_u64 v[146:147], v[130:131], 0, s[42:43]
	global_load_dwordx4 v[142:145], v[132:133], off
	global_load_dwordx4 v[138:141], v[132:133], off offset:64
	global_load_dwordx4 v[208:211], v[146:147], off
	global_load_dwordx4 v[216:219], v[146:147], off offset:64
	global_load_dwordx4 v[134:137], v[132:133], off offset:128
	s_nop 0
	global_load_dwordx4 v[130:133], v[132:133], off offset:192
	s_nop 0
	global_load_dwordx4 v[240:243], v[146:147], off offset:128
	global_load_dwordx4 v[244:247], v[146:147], off offset:192
	s_mov_b64 s[0:1], 0x10000
	v_lshl_add_u64 v[148:149], v[146:147], 0, s[0:1]
	s_mov_b32 s0, 0x10000
	v_add_co_u32_e32 v150, vcc, s0, v146
	s_mov_b64 s[0:1], 0x20000
	s_nop 0
	v_addc_co_u32_e32 v151, vcc, 0, v147, vcc
	global_load_dwordx4 v[186:189], v[148:149], off offset:64
	global_load_dwordx4 v[182:185], v[148:149], off offset:128
	global_load_dwordx4 v[190:193], v[150:151], off
	global_load_dwordx4 v[178:181], v[148:149], off offset:192
	v_lshl_add_u64 v[148:149], v[146:147], 0, s[0:1]
	s_mov_b32 s0, 0x20000
	v_add_co_u32_e32 v150, vcc, s0, v146
	s_mov_b64 s[0:1], 0x30000
	s_nop 0
	v_addc_co_u32_e32 v151, vcc, 0, v147, vcc
	global_load_dwordx4 v[170:173], v[148:149], off offset:64
	global_load_dwordx4 v[166:169], v[148:149], off offset:128
	global_load_dwordx4 v[174:177], v[150:151], off
	global_load_dwordx4 v[162:165], v[148:149], off offset:192
	v_lshl_add_u64 v[148:149], v[146:147], 0, s[0:1]
	s_mov_b32 s0, 0x30000
	v_add_co_u32_e32 v146, vcc, s0, v146
	v_add_u32_e32 v248, s85, v237
	s_nop 0
	v_addc_co_u32_e32 v147, vcc, 0, v147, vcc
	global_load_dwordx4 v[154:157], v[148:149], off offset:64
	global_load_dwordx4 v[150:153], v[148:149], off offset:128
	global_load_dwordx4 v[158:161], v[146:147], off
	s_nop 0
	global_load_dwordx4 v[146:149], v[148:149], off offset:192
	v_readfirstlane_b32 s57, v238
	v_cmp_eq_u32_e64 s[0:1], 0, v236
	s_waitcnt vmcnt(12)
	v_pk_fma_f32 v[214:215], v[128:129], v[144:145], v[210:211]
	v_pk_fma_f32 v[222:223], v[126:127], v[142:143], v[208:209]
	v_pk_fma_f32 v[212:213], v[124:125], v[140:141], v[218:219]
	v_pk_fma_f32 v[220:221], v[122:123], v[138:139], v[216:217]
	v_pk_fma_f32 v[210:211], v[120:121], v[136:137], v[242:243]
	v_pk_fma_f32 v[218:219], v[118:119], v[134:135], v[240:241]
	v_pk_fma_f32 v[208:209], v[116:117], v[132:133], v[246:247]
	v_pk_fma_f32 v[216:217], v[114:115], v[130:131], v[244:245]
	v_mul_f32_e32 v114, v223, v223
	v_mul_f32_e32 v115, v215, v215
	v_mul_f32_e32 v116, v221, v221
	v_mul_f32_e32 v117, v213, v213
	v_mul_f32_e32 v118, v219, v219
	v_mul_f32_e32 v119, v211, v211
	v_fmac_f32_e32 v114, v222, v222
	v_fmac_f32_e32 v115, v214, v214
	v_fmac_f32_e32 v116, v220, v220
	v_fmac_f32_e32 v117, v212, v212
	v_mul_f32_e32 v120, v217, v217
	v_mul_f32_e32 v121, v209, v209
	v_fmac_f32_e32 v118, v218, v218
	v_fmac_f32_e32 v119, v210, v210
	v_add_f32_e32 v114, v114, v115
	v_add_f32_e32 v115, v116, v117
	v_fmac_f32_e32 v120, v216, v216
	v_fmac_f32_e32 v121, v208, v208
	v_add_f32_e32 v116, v118, v119
	v_add_f32_e32 v114, v114, v115
	v_add_f32_e32 v117, v120, v121
	v_add_f32_e32 v114, v114, v116
	v_add_f32_e32 v114, v114, v117
	v_mov_b32_e32 v115, v114
	s_nop 1
	v_permlane16_swap_b32_e32 v114, v115
	v_add_f32_e32 v114, v114, v115
	v_mov_b32_e32 v115, v114
	s_nop 1
	v_permlane32_swap_b32_e32 v114, v115
	v_lshl_add_u32 v240, v248, 4, s92
	s_and_saveexec_b64 s[8:9], s[0:1]
	v_add_f32_e32 v114, v114, v115
	ds_write_b32 v240, v114
	s_or_b64 exec, exec, s[8:9]
	s_waitcnt vmcnt(0)
	v_pk_fma_f32 v[192:193], v[112:113], v[144:145], v[192:193]
	v_pk_fma_f32 v[190:191], v[110:111], v[142:143], v[190:191]
	v_pk_fma_f32 v[188:189], v[108:109], v[140:141], v[188:189]
	v_pk_fma_f32 v[186:187], v[106:107], v[138:139], v[186:187]
	v_mul_f32_e32 v110, v191, v191
	v_mul_f32_e32 v111, v193, v193
	v_mul_f32_e32 v106, v187, v187
	v_mul_f32_e32 v107, v189, v189
	v_pk_fma_f32 v[184:185], v[104:105], v[136:137], v[184:185]
	v_pk_fma_f32 v[182:183], v[102:103], v[134:135], v[182:183]
	v_fmac_f32_e32 v110, v190, v190
	v_fmac_f32_e32 v111, v192, v192
	v_fmac_f32_e32 v106, v186, v186
	v_fmac_f32_e32 v107, v188, v188
	v_mul_f32_e32 v102, v183, v183
	v_mul_f32_e32 v103, v185, v185
	v_pk_fma_f32 v[180:181], v[100:101], v[132:133], v[180:181]
	v_pk_fma_f32 v[178:179], v[98:99], v[130:131], v[178:179]
	v_add_f32_e32 v110, v110, v111
	v_add_f32_e32 v106, v106, v107
	v_fmac_f32_e32 v102, v182, v182
	v_fmac_f32_e32 v103, v184, v184
	v_mul_f32_e32 v98, v179, v179
	v_mul_f32_e32 v99, v181, v181
	v_add_f32_e32 v106, v110, v106
	v_add_f32_e32 v102, v102, v103
	v_fmac_f32_e32 v98, v178, v178
	v_fmac_f32_e32 v99, v180, v180
	v_add_f32_e32 v102, v106, v102
	v_add_f32_e32 v98, v98, v99
	v_add_f32_e32 v98, v102, v98
	v_mov_b32_e32 v99, v98
	s_nop 1
	v_permlane16_swap_b32_e32 v98, v99
	v_add_f32_e32 v98, v98, v99
	v_mov_b32_e32 v99, v98
	s_nop 1
	v_permlane32_swap_b32_e32 v98, v99
	s_and_saveexec_b64 s[8:9], s[0:1]
	v_add_f32_e32 v98, v98, v99
	ds_write_b32 v240, v98 offset:256
	s_or_b64 exec, exec, s[8:9]
	v_pk_fma_f32 v[176:177], v[96:97], v[144:145], v[176:177]
	v_pk_fma_f32 v[174:175], v[94:95], v[142:143], v[174:175]
	v_pk_fma_f32 v[172:173], v[92:93], v[140:141], v[172:173]
	v_pk_fma_f32 v[170:171], v[90:91], v[138:139], v[170:171]
	v_mul_f32_e32 v94, v175, v175
	v_mul_f32_e32 v95, v177, v177
	v_mul_f32_e32 v90, v171, v171
	v_mul_f32_e32 v91, v173, v173
	v_pk_fma_f32 v[168:169], v[88:89], v[136:137], v[168:169]
	v_pk_fma_f32 v[166:167], v[86:87], v[134:135], v[166:167]
	v_fmac_f32_e32 v94, v174, v174
	v_fmac_f32_e32 v95, v176, v176
	v_fmac_f32_e32 v90, v170, v170
	v_fmac_f32_e32 v91, v172, v172
	v_mul_f32_e32 v86, v167, v167
	v_mul_f32_e32 v87, v169, v169
	v_pk_fma_f32 v[164:165], v[84:85], v[132:133], v[164:165]
	v_pk_fma_f32 v[162:163], v[82:83], v[130:131], v[162:163]
	v_add_f32_e32 v94, v94, v95
	v_add_f32_e32 v90, v90, v91
	v_fmac_f32_e32 v86, v166, v166
	v_fmac_f32_e32 v87, v168, v168
	v_mul_f32_e32 v82, v163, v163
	v_mul_f32_e32 v83, v165, v165
	v_add_f32_e32 v90, v94, v90
	v_add_f32_e32 v86, v86, v87
	v_fmac_f32_e32 v82, v162, v162
	v_fmac_f32_e32 v83, v164, v164
	v_add_f32_e32 v86, v90, v86
	v_add_f32_e32 v82, v82, v83
	v_add_f32_e32 v82, v86, v82
	v_mov_b32_e32 v83, v82
	s_nop 1
	v_permlane16_swap_b32_e32 v82, v83
	v_add_f32_e32 v82, v82, v83
	v_mov_b32_e32 v83, v82
	s_nop 1
	v_permlane32_swap_b32_e32 v82, v83
	s_and_saveexec_b64 s[8:9], s[0:1]
	v_add_f32_e32 v82, v82, v83
	ds_write_b32 v240, v82 offset:512
	s_or_b64 exec, exec, s[8:9]
	v_pk_fma_f32 v[120:121], v[80:81], v[144:145], v[160:161]
	v_pk_fma_f32 v[128:129], v[78:79], v[142:143], v[158:159]
	v_pk_fma_f32 v[118:119], v[76:77], v[140:141], v[156:157]
	v_pk_fma_f32 v[126:127], v[74:75], v[138:139], v[154:155]
	v_mul_f32_e32 v78, v129, v129
	v_mul_f32_e32 v79, v121, v121
	v_mul_f32_e32 v74, v127, v127
	v_mul_f32_e32 v75, v119, v119
	v_pk_fma_f32 v[116:117], v[72:73], v[136:137], v[152:153]
	v_pk_fma_f32 v[124:125], v[70:71], v[134:135], v[150:151]
	v_fmac_f32_e32 v78, v128, v128
	v_fmac_f32_e32 v79, v120, v120
	v_fmac_f32_e32 v74, v126, v126
	v_fmac_f32_e32 v75, v118, v118
	v_mul_f32_e32 v70, v125, v125
	v_mul_f32_e32 v71, v117, v117
	v_pk_fma_f32 v[114:115], v[68:69], v[132:133], v[148:149]
	v_pk_fma_f32 v[122:123], v[66:67], v[130:131], v[146:147]
	v_add_f32_e32 v78, v78, v79
	v_add_f32_e32 v74, v74, v75
	v_fmac_f32_e32 v70, v124, v124
	v_fmac_f32_e32 v71, v116, v116
	v_mul_f32_e32 v66, v123, v123
	v_mul_f32_e32 v67, v115, v115
	v_add_f32_e32 v74, v78, v74
	v_add_f32_e32 v70, v70, v71
	v_fmac_f32_e32 v66, v122, v122
	v_fmac_f32_e32 v67, v114, v114
	v_add_f32_e32 v70, v74, v70
	v_add_f32_e32 v66, v66, v67
	v_add_f32_e32 v66, v70, v66
	v_mov_b32_e32 v67, v66
	s_nop 1
	v_permlane16_swap_b32_e32 v66, v67
	v_add_f32_e32 v66, v66, v67
	v_mov_b32_e32 v67, v66
	s_nop 1
	v_permlane32_swap_b32_e32 v66, v67
	s_and_saveexec_b64 s[8:9], s[0:1]
	v_add_f32_e32 v66, v66, v67
	ds_write_b32 v240, v66 offset:768
	s_or_b64 exec, exec, s[8:9]
	v_lshlrev_b64 v[66:67], 12, v[224:225]
	v_lshl_add_u64 v[66:67], v[226:227], 0, v[66:67]
	v_lshl_add_u64 v[66:67], v[66:67], 0, s[42:43]
	s_mov_b64 s[6:7], 0x80000
	v_lshl_add_u64 v[68:69], v[66:67], 0, s[6:7]
	v_add_co_u32_e32 v70, vcc, 0x80000, v66
	global_load_dwordx4 v[146:149], v[68:69], off offset:64
	global_load_dwordx4 v[150:153], v[68:69], off offset:128
	v_addc_co_u32_e32 v71, vcc, 0, v67, vcc
	global_load_dwordx4 v[154:157], v[70:71], off
	global_load_dwordx4 v[158:161], v[68:69], off offset:192
	s_mov_b64 s[6:7], 0x90000
	v_add_co_u32_e32 v70, vcc, 0x90000, v66
	v_lshl_add_u64 v[68:69], v[66:67], 0, s[6:7]
	s_nop 0
	v_addc_co_u32_e32 v71, vcc, 0, v67, vcc
	global_load_dwordx4 v[106:109], v[68:69], off offset:64
	global_load_dwordx4 v[102:105], v[68:69], off offset:128
	global_load_dwordx4 v[110:113], v[70:71], off
	global_load_dwordx4 v[98:101], v[68:69], off offset:192
	s_mov_b64 s[6:7], 0xa0000
	v_add_co_u32_e32 v70, vcc, 0xa0000, v66
	v_lshl_add_u64 v[68:69], v[66:67], 0, s[6:7]
	s_nop 0
	v_addc_co_u32_e32 v71, vcc, 0, v67, vcc
	s_mov_b64 s[6:7], 0xb0000
	global_load_dwordx4 v[90:93], v[68:69], off offset:64
	global_load_dwordx4 v[86:89], v[68:69], off offset:128
	global_load_dwordx4 v[94:97], v[70:71], off
	global_load_dwordx4 v[82:85], v[68:69], off offset:192
	v_lshl_add_u64 v[68:69], v[66:67], 0, s[6:7]
	v_add_co_u32_e32 v66, vcc, 0xb0000, v66
	s_waitcnt vmcnt(11)
	v_pk_fma_f32 v[64:65], v[64:65], v[140:141], v[148:149]
	v_addc_co_u32_e32 v67, vcc, 0, v67, vcc
	global_load_dwordx4 v[74:77], v[68:69], off offset:64
	global_load_dwordx4 v[70:73], v[68:69], off offset:128
	global_load_dwordx4 v[78:81], v[66:67], off
	s_nop 0
	global_load_dwordx4 v[66:69], v[68:69], off offset:192
	v_pk_fma_f32 v[62:63], v[62:63], v[138:139], v[146:147]
	s_waitcnt vmcnt(14)
	v_pk_fma_f32 v[54:55], v[54:55], v[134:135], v[150:151]
	s_waitcnt vmcnt(13)
	v_pk_fma_f32 v[148:149], v[60:61], v[144:145], v[156:157]
	v_pk_fma_f32 v[150:151], v[58:59], v[142:143], v[154:155]
	v_pk_fma_f32 v[56:57], v[56:57], v[136:137], v[152:153]
	v_mul_f32_e32 v58, v63, v63
	v_mul_f32_e32 v59, v65, v65
	s_waitcnt vmcnt(12)
	v_pk_fma_f32 v[146:147], v[50:51], v[130:131], v[158:159]
	v_mul_f32_e32 v50, v151, v151
	v_mul_f32_e32 v51, v149, v149
	v_mul_f32_e32 v60, v55, v55
	v_mul_f32_e32 v61, v57, v57
	v_pk_fma_f32 v[52:53], v[52:53], v[132:133], v[160:161]
	v_fmac_f32_e32 v58, v62, v62
	v_fmac_f32_e32 v59, v64, v64
	v_fmac_f32_e32 v50, v150, v150
	v_fmac_f32_e32 v51, v148, v148
	v_fmac_f32_e32 v60, v54, v54
	v_fmac_f32_e32 v61, v56, v56
	v_mul_f32_e32 v152, v147, v147
	v_mul_f32_e32 v153, v53, v53
	v_add_f32_e32 v58, v58, v59
	v_add_f32_e32 v50, v50, v51
	v_add_f32_e32 v59, v60, v61
	v_fmac_f32_e32 v152, v146, v146
	v_fmac_f32_e32 v153, v52, v52
	v_add_f32_e32 v50, v50, v58
	v_add_f32_e32 v51, v152, v153
	v_add_f32_e32 v50, v50, v59
	v_add_f32_e32 v50, v50, v51
	v_mov_b32_e32 v51, v50
	s_nop 1
	v_permlane16_swap_b32_e32 v50, v51
	v_add_f32_e32 v50, v50, v51
	v_mov_b32_e32 v51, v50
	s_nop 1
	v_permlane32_swap_b32_e32 v50, v51
	s_and_saveexec_b64 s[8:9], s[0:1]
	v_add_f32_e32 v50, v50, v51
	ds_write_b32 v240, v50 offset:2048
	s_or_b64 exec, exec, s[8:9]
	s_waitcnt vmcnt(9)
	v_pk_fma_f32 v[112:113], v[48:49], v[144:145], v[112:113]
	v_pk_fma_f32 v[110:111], v[46:47], v[142:143], v[110:111]
	v_pk_fma_f32 v[60:61], v[44:45], v[140:141], v[108:109]
	v_pk_fma_f32 v[106:107], v[42:43], v[138:139], v[106:107]
	v_mul_f32_e32 v46, v111, v111
	v_mul_f32_e32 v47, v113, v113
	v_mul_f32_e32 v42, v107, v107
	v_mul_f32_e32 v43, v61, v61
	v_pk_fma_f32 v[58:59], v[40:41], v[136:137], v[104:105]
	v_pk_fma_f32 v[102:103], v[38:39], v[134:135], v[102:103]
	v_fmac_f32_e32 v46, v110, v110
	v_fmac_f32_e32 v47, v112, v112
	v_fmac_f32_e32 v42, v106, v106
	v_fmac_f32_e32 v43, v60, v60
	v_mul_f32_e32 v38, v103, v103
	v_mul_f32_e32 v39, v59, v59
	s_waitcnt vmcnt(8)
	v_pk_fma_f32 v[50:51], v[36:37], v[132:133], v[100:101]
	v_pk_fma_f32 v[98:99], v[34:35], v[130:131], v[98:99]
	v_add_f32_e32 v46, v46, v47
	v_add_f32_e32 v42, v42, v43
	v_fmac_f32_e32 v38, v102, v102
	v_fmac_f32_e32 v39, v58, v58
	v_mul_f32_e32 v34, v99, v99
	v_mul_f32_e32 v35, v51, v51
	v_add_f32_e32 v42, v46, v42
	v_add_f32_e32 v38, v38, v39
	v_fmac_f32_e32 v34, v98, v98
	v_fmac_f32_e32 v35, v50, v50
	v_add_f32_e32 v38, v42, v38
	v_add_f32_e32 v34, v34, v35
	v_add_f32_e32 v34, v38, v34
	v_mov_b32_e32 v35, v34
	s_nop 1
	v_permlane16_swap_b32_e32 v34, v35
	v_add_f32_e32 v34, v34, v35
	v_mov_b32_e32 v35, v34
	s_nop 1
	v_permlane32_swap_b32_e32 v34, v35
	s_and_saveexec_b64 s[8:9], s[0:1]
	v_add_f32_e32 v34, v34, v35
	ds_write_b32 v240, v34 offset:2304
	s_or_b64 exec, exec, s[8:9]
	s_waitcnt vmcnt(5)
	v_pk_fma_f32 v[36:37], v[32:33], v[144:145], v[96:97]
	v_pk_fma_f32 v[44:45], v[30:31], v[142:143], v[94:95]
	v_pk_fma_f32 v[34:35], v[28:29], v[140:141], v[92:93]
	v_pk_fma_f32 v[42:43], v[26:27], v[138:139], v[90:91]
	v_mul_f32_e32 v30, v45, v45
	v_mul_f32_e32 v31, v37, v37
	v_mul_f32_e32 v26, v43, v43
	v_mul_f32_e32 v27, v35, v35
	v_pk_fma_f32 v[38:39], v[24:25], v[136:137], v[88:89]
	v_pk_fma_f32 v[46:47], v[22:23], v[134:135], v[86:87]
	v_fmac_f32_e32 v30, v44, v44
	v_fmac_f32_e32 v31, v36, v36
	v_fmac_f32_e32 v26, v42, v42
	v_fmac_f32_e32 v27, v34, v34
	v_mul_f32_e32 v22, v47, v47
	v_mul_f32_e32 v23, v39, v39
	s_waitcnt vmcnt(4)
	v_pk_fma_f32 v[40:41], v[20:21], v[132:133], v[84:85]
	v_pk_fma_f32 v[48:49], v[18:19], v[130:131], v[82:83]
	v_add_f32_e32 v30, v30, v31
	v_add_f32_e32 v26, v26, v27
	v_fmac_f32_e32 v22, v46, v46
	v_fmac_f32_e32 v23, v38, v38
	v_mul_f32_e32 v18, v49, v49
	v_mul_f32_e32 v19, v41, v41
	v_add_f32_e32 v26, v30, v26
	v_add_f32_e32 v22, v22, v23
	v_fmac_f32_e32 v18, v48, v48
	v_fmac_f32_e32 v19, v40, v40
	v_add_f32_e32 v22, v26, v22
	v_add_f32_e32 v18, v18, v19
	v_add_f32_e32 v18, v22, v18
	v_mov_b32_e32 v19, v18
	s_nop 1
	v_permlane16_swap_b32_e32 v18, v19
	v_add_f32_e32 v18, v18, v19
	v_mov_b32_e32 v19, v18
	s_nop 1
	v_permlane32_swap_b32_e32 v18, v19
	s_and_saveexec_b64 s[8:9], s[0:1]
	v_add_f32_e32 v18, v18, v19
	ds_write_b32 v240, v18 offset:2560
	s_or_b64 exec, exec, s[8:9]
	s_waitcnt vmcnt(1)
	v_pk_fma_f32 v[24:25], v[16:17], v[144:145], v[80:81]
	v_pk_fma_f32 v[32:33], v[14:15], v[142:143], v[78:79]
	v_pk_fma_f32 v[22:23], v[12:13], v[140:141], v[76:77]
	v_pk_fma_f32 v[30:31], v[10:11], v[138:139], v[74:75]
	v_mul_f32_e32 v14, v33, v33
	v_mul_f32_e32 v15, v25, v25
	v_mul_f32_e32 v10, v31, v31
	v_mul_f32_e32 v11, v23, v23
	v_pk_fma_f32 v[20:21], v[8:9], v[136:137], v[72:73]
	v_pk_fma_f32 v[28:29], v[6:7], v[134:135], v[70:71]
	v_fmac_f32_e32 v14, v32, v32
	v_fmac_f32_e32 v15, v24, v24
	v_fmac_f32_e32 v10, v30, v30
	v_fmac_f32_e32 v11, v22, v22
	v_mul_f32_e32 v6, v29, v29
	v_mul_f32_e32 v7, v21, v21
	s_waitcnt vmcnt(0)
	v_pk_fma_f32 v[18:19], v[4:5], v[132:133], v[68:69]
	v_pk_fma_f32 v[26:27], v[2:3], v[130:131], v[66:67]
	v_add_f32_e32 v14, v14, v15
	v_add_f32_e32 v10, v10, v11
	v_fmac_f32_e32 v6, v28, v28
	v_fmac_f32_e32 v7, v20, v20
	v_mul_f32_e32 v2, v27, v27
	v_mul_f32_e32 v3, v19, v19
	v_add_f32_e32 v10, v14, v10
	v_add_f32_e32 v6, v6, v7
	v_fmac_f32_e32 v2, v26, v26
	v_fmac_f32_e32 v3, v18, v18
	v_add_f32_e32 v6, v10, v6
	v_add_f32_e32 v2, v2, v3
	v_add_f32_e32 v2, v6, v2
	v_mov_b32_e32 v3, v2
	s_nop 1
	v_permlane16_swap_b32_e32 v2, v3
	v_add_f32_e32 v2, v2, v3
	v_mov_b32_e32 v3, v2
	s_nop 1
	v_permlane32_swap_b32_e32 v2, v3
	s_and_saveexec_b64 s[8:9], s[0:1]
	v_add_f32_e32 v2, v2, v3
	ds_write_b32 v240, v2 offset:2816
	s_or_b64 exec, exec, s[8:9]
	s_ashr_i32 s6, s57, 6
	v_and_b32_e32 v2, 31, v238
	s_waitcnt lgkmcnt(0)
	s_barrier
	v_lshl_or_b32 v4, s6, 5, v2
	v_and_b32_e32 v68, 63, v238
	v_add_u32_e32 v2, s10, v4
	v_cmp_gt_u32_e64 s[0:1], 32, v68
	v_ashrrev_i32_e32 v3, 31, v2
	s_and_saveexec_b64 s[8:9], s[0:1]
	s_cbranch_execz .LBB0_683
	v_lshl_add_u32 v5, v4, 4, 0
	v_add_u32_e32 v5, 0x20000, v5
	ds_read_b128 v[6:9], v5
	v_lshl_add_u64 v[10:11], v[2:3], 4, s[48:49]
	s_ashr_i32 s63, s62, 31
	v_lshl_add_u64 v[10:11], s[62:63], 2, v[10:11]
	s_waitcnt lgkmcnt(0)
	v_mov_b32_e32 v12, v7
	v_mov_b32_e32 v13, v8
	v_mov_b32_e32 v7, v9
	v_pk_add_f32 v[6:7], v[12:13], v[6:7]
	s_nop 0
	v_pk_add_f32 v[6:7], v[6:7], v[6:7] op_sel:[0,1] op_sel_hi:[1,0]
	global_store_dword v[10:11], v6, off sc1

.LBB0_858:
	v_mov_b32_e32 v199, v190
	v_mov_b32_e32 v161, v0
	v_mov_b32_e32 v198, v191
	s_ashr_i32 s4, s56, 3
	s_lshl_b32 s7, s56, 8
	s_add_i32 s49, s7, s73
	s_lshl_b32 s51, s6, 8
	v_lshlrev_b32_e32 v160, 2, v198
	s_mul_hi_i32 s5, s4, 0x6000
	s_mulk_i32 s4, 0x6000
	v_add_u32_e32 v118, s51, v160
	s_add_u32 s4, s69, s4
	v_add_u32_e32 v162, s49, v199
	s_addc_u32 s5, s70, s5
	v_ashrrev_i32_e32 v119, 31, v118
	v_ashrrev_i32_e32 v163, 31, v162
	v_lshl_add_u64 v[120:121], v[118:119], 2, s[4:5]
	s_lshl_b32 s10, s74, 2
	v_lshl_add_u64 v[164:165], v[118:119], 1, s[40:41]
	v_lshlrev_b64 v[118:119], 11, v[162:163]
	v_lshl_add_u64 v[120:121], v[120:121], 0, s[10:11]
	v_lshl_add_u64 v[118:119], v[164:165], 0, v[118:119]
	s_lshl_b32 s10, s74, 1
	v_lshl_add_u64 v[166:167], v[118:119], 0, s[10:11]
	v_add_co_u32_e32 v170, vcc, s78, v166
	global_load_dwordx2 v[200:201], v[166:167], off
	global_load_dwordx2 v[202:203], v[166:167], off offset:32
	global_load_dwordx2 v[204:205], v[166:167], off offset:256
	global_load_dwordx2 v[206:207], v[166:167], off offset:288
	global_load_dwordx4 v[134:137], v[120:121], off
	global_load_dwordx4 v[130:133], v[120:121], off offset:64
	global_load_dwordx4 v[126:129], v[120:121], off offset:512
	s_nop 0
	global_load_dwordx4 v[118:121], v[120:121], off offset:576
	v_addc_co_u32_e32 v171, vcc, 0, v167, vcc
	v_add_co_u32_e32 v174, vcc, s68, v166
	v_lshl_add_u64 v[168:169], v[166:167], 0, s[30:31]
	s_nop 0
	v_addc_co_u32_e32 v175, vcc, 0, v167, vcc
	v_lshl_add_u64 v[172:173], v[166:167], 0, s[34:35]
	v_lshl_add_u64 v[208:209], v[166:167], 0, s[36:37]
	v_add_co_u32_e32 v166, vcc, s77, v166
	v_add_u32_e32 v218, s73, v199
	s_nop 0
	v_addc_co_u32_e32 v167, vcc, 0, v167, vcc
	global_load_dwordx2 v[188:189], v[170:171], off
	global_load_dwordx2 v[186:187], v[168:169], off offset:32
	global_load_dwordx2 v[184:185], v[168:169], off offset:256
	global_load_dwordx2 v[182:183], v[168:169], off offset:288
	global_load_dwordx2 v[180:181], v[174:175], off
	global_load_dwordx2 v[178:179], v[172:173], off offset:32
	global_load_dwordx2 v[176:177], v[172:173], off offset:256
	s_nop 0
	global_load_dwordx2 v[174:175], v[172:173], off offset:288
	s_nop 0
	global_load_dwordx2 v[172:173], v[166:167], off
	global_load_dwordx2 v[170:171], v[208:209], off offset:32
	global_load_dwordx2 v[168:169], v[208:209], off offset:256
	s_nop 0
	global_load_dwordx2 v[166:167], v[208:209], off offset:288
	v_readfirstlane_b32 s57, v161
	v_cmp_eq_u32_e64 s[4:5], 0, v198
	s_waitcnt vmcnt(12)
	v_and_b32_e32 v209, 0xffff0000, v200
	v_lshlrev_b32_e32 v208, 16, v200
	v_and_b32_e32 v211, 0xffff0000, v201
	v_lshlrev_b32_e32 v210, 16, v201
	v_and_b32_e32 v201, 0xffff0000, v202
	v_lshlrev_b32_e32 v200, 16, v202
	v_and_b32_e32 v213, 0xffff0000, v203
	v_lshlrev_b32_e32 v212, 16, v203
	v_pk_fma_f32 v[144:145], v[144:145], v[136:137], v[210:211]
	v_pk_fma_f32 v[142:143], v[142:143], v[134:135], v[208:209]
	v_pk_fma_f32 v[140:141], v[140:141], v[132:133], v[212:213]
	v_pk_fma_f32 v[138:139], v[138:139], v[130:131], v[200:201]
	v_and_b32_e32 v203, 0xffff0000, v204
	v_lshlrev_b32_e32 v202, 16, v204
	v_and_b32_e32 v215, 0xffff0000, v205
	v_lshlrev_b32_e32 v214, 16, v205
	v_and_b32_e32 v205, 0xffff0000, v206
	v_lshlrev_b32_e32 v204, 16, v206
	v_and_b32_e32 v217, 0xffff0000, v207
	v_lshlrev_b32_e32 v216, 16, v207
	v_mul_f32_e32 v200, v143, v143
	v_mul_f32_e32 v201, v145, v145
	v_mul_f32_e32 v206, v139, v139
	v_mul_f32_e32 v207, v141, v141
	v_fmac_f32_e32 v200, v142, v142
	v_fmac_f32_e32 v201, v144, v144
	v_fmac_f32_e32 v206, v138, v138
	v_fmac_f32_e32 v207, v140, v140
	v_add_f32_e32 v200, v200, v201
	v_add_f32_e32 v201, v206, v207
	v_pk_fma_f32 v[124:125], v[124:125], v[128:129], v[214:215]
	v_pk_fma_f32 v[122:123], v[122:123], v[126:127], v[202:203]
	v_add_f32_e32 v200, v200, v201
	v_mul_f32_e32 v201, v123, v123
	v_mul_f32_e32 v202, v125, v125
	v_fmac_f32_e32 v201, v122, v122
	v_fmac_f32_e32 v202, v124, v124
	v_add_f32_e32 v201, v201, v202
	v_pk_fma_f32 v[116:117], v[116:117], v[120:121], v[216:217]
	v_pk_fma_f32 v[114:115], v[114:115], v[118:119], v[204:205]
	v_add_f32_e32 v200, v200, v201
	v_mul_f32_e32 v201, v115, v115
	v_mul_f32_e32 v202, v117, v117
	v_fmac_f32_e32 v201, v114, v114
	v_fmac_f32_e32 v202, v116, v116
	v_add_f32_e32 v201, v201, v202
	v_add_f32_e32 v200, v200, v201
	v_mov_b32_e32 v201, v200
	s_nop 1
	v_permlane16_swap_b32_e32 v200, v201
	v_add_f32_e32 v201, v200, v201
	v_mov_b32_e32 v202, v201
	s_nop 1
	v_permlane32_swap_b32_e32 v201, v202
	v_lshl_add_u32 v200, v218, 4, s81
	s_and_saveexec_b64 s[8:9], s[4:5]
	v_add_f32_e32 v201, v201, v202
	ds_write_b32 v200, v201
	s_or_b64 exec, exec, s[8:9]
	s_waitcnt vmcnt(0)
	v_and_b32_e32 v203, 0xffff0000, v188
	v_and_b32_e32 v205, 0xffff0000, v189
	v_lshlrev_b32_e32 v202, 16, v188
	v_lshlrev_b32_e32 v204, 16, v189
	v_pk_fma_f32 v[112:113], v[112:113], v[136:137], v[204:205]
	v_pk_fma_f32 v[110:111], v[110:111], v[134:135], v[202:203]
	v_and_b32_e32 v189, 0xffff0000, v186
	v_and_b32_e32 v207, 0xffff0000, v187
	v_lshlrev_b32_e32 v188, 16, v186
	v_lshlrev_b32_e32 v206, 16, v187
	v_and_b32_e32 v187, 0xffff0000, v184
	v_and_b32_e32 v209, 0xffff0000, v185
	v_lshlrev_b32_e32 v186, 16, v184
	v_lshlrev_b32_e32 v208, 16, v185
	v_and_b32_e32 v185, 0xffff0000, v182
	v_and_b32_e32 v211, 0xffff0000, v183
	v_lshlrev_b32_e32 v184, 16, v182
	v_lshlrev_b32_e32 v210, 16, v183
	v_mul_f32_e32 v182, v111, v111
	v_mul_f32_e32 v183, v113, v113
	v_fmac_f32_e32 v182, v110, v110
	v_fmac_f32_e32 v183, v112, v112
	v_pk_fma_f32 v[108:109], v[108:109], v[132:133], v[206:207]
	v_pk_fma_f32 v[106:107], v[106:107], v[130:131], v[188:189]
	v_add_f32_e32 v182, v182, v183
	v_mul_f32_e32 v183, v107, v107
	v_mul_f32_e32 v188, v109, v109
	v_fmac_f32_e32 v183, v106, v106
	v_fmac_f32_e32 v188, v108, v108
	v_add_f32_e32 v183, v183, v188
	v_pk_fma_f32 v[104:105], v[104:105], v[128:129], v[208:209]
	v_pk_fma_f32 v[102:103], v[102:103], v[126:127], v[186:187]
	v_add_f32_e32 v182, v182, v183
	v_mul_f32_e32 v183, v103, v103
	v_mul_f32_e32 v186, v105, v105
	v_fmac_f32_e32 v183, v102, v102
	v_fmac_f32_e32 v186, v104, v104
	v_add_f32_e32 v183, v183, v186
	v_pk_fma_f32 v[100:101], v[100:101], v[120:121], v[210:211]
	v_pk_fma_f32 v[98:99], v[98:99], v[118:119], v[184:185]
	v_add_f32_e32 v182, v182, v183
	v_mul_f32_e32 v183, v99, v99
	v_mul_f32_e32 v184, v101, v101
	v_fmac_f32_e32 v183, v98, v98
	v_fmac_f32_e32 v184, v100, v100
	v_add_f32_e32 v183, v183, v184
	v_add_f32_e32 v182, v182, v183
	v_mov_b32_e32 v183, v182
	s_nop 1
	v_permlane16_swap_b32_e32 v182, v183
	v_add_f32_e32 v182, v182, v183
	v_mov_b32_e32 v183, v182
	s_nop 1
	v_permlane32_swap_b32_e32 v182, v183
	s_and_saveexec_b64 s[8:9], s[4:5]
	v_add_f32_e32 v182, v182, v183
	ds_write_b32 v200, v182 offset:256
	s_or_b64 exec, exec, s[8:9]
	v_and_b32_e32 v183, 0xffff0000, v180
	v_and_b32_e32 v185, 0xffff0000, v181
	v_lshlrev_b32_e32 v182, 16, v180
	v_lshlrev_b32_e32 v184, 16, v181
	v_pk_fma_f32 v[96:97], v[96:97], v[136:137], v[184:185]
	v_pk_fma_f32 v[94:95], v[94:95], v[134:135], v[182:183]
	v_and_b32_e32 v181, 0xffff0000, v178
	v_and_b32_e32 v187, 0xffff0000, v179
	v_lshlrev_b32_e32 v180, 16, v178
	v_lshlrev_b32_e32 v186, 16, v179
	v_and_b32_e32 v179, 0xffff0000, v176
	v_and_b32_e32 v189, 0xffff0000, v177
	v_lshlrev_b32_e32 v178, 16, v176
	v_lshlrev_b32_e32 v188, 16, v177
	v_and_b32_e32 v177, 0xffff0000, v174
	v_and_b32_e32 v203, 0xffff0000, v175
	v_lshlrev_b32_e32 v176, 16, v174
	v_lshlrev_b32_e32 v202, 16, v175
	v_mul_f32_e32 v174, v95, v95
	v_mul_f32_e32 v175, v97, v97
	v_fmac_f32_e32 v174, v94, v94
	v_fmac_f32_e32 v175, v96, v96
	v_pk_fma_f32 v[92:93], v[92:93], v[132:133], v[186:187]
	v_pk_fma_f32 v[90:91], v[90:91], v[130:131], v[180:181]
	v_add_f32_e32 v174, v174, v175
	v_mul_f32_e32 v175, v91, v91
	v_mul_f32_e32 v180, v93, v93
	v_fmac_f32_e32 v175, v90, v90
	v_fmac_f32_e32 v180, v92, v92
	v_add_f32_e32 v175, v175, v180
	v_pk_fma_f32 v[88:89], v[88:89], v[128:129], v[188:189]
	v_pk_fma_f32 v[86:87], v[86:87], v[126:127], v[178:179]
	v_add_f32_e32 v174, v174, v175
	v_mul_f32_e32 v175, v87, v87
	v_mul_f32_e32 v178, v89, v89
	v_fmac_f32_e32 v175, v86, v86
	v_fmac_f32_e32 v178, v88, v88
	v_add_f32_e32 v175, v175, v178
	v_pk_fma_f32 v[84:85], v[84:85], v[120:121], v[202:203]
	v_pk_fma_f32 v[82:83], v[82:83], v[118:119], v[176:177]
	v_add_f32_e32 v174, v174, v175
	v_mul_f32_e32 v175, v83, v83
	v_mul_f32_e32 v176, v85, v85
	v_fmac_f32_e32 v175, v82, v82
	v_fmac_f32_e32 v176, v84, v84
	v_add_f32_e32 v175, v175, v176
	v_add_f32_e32 v174, v174, v175
	v_mov_b32_e32 v175, v174
	s_nop 1
	v_permlane16_swap_b32_e32 v174, v175
	v_add_f32_e32 v174, v174, v175
	v_mov_b32_e32 v175, v174
	s_nop 1
	v_permlane32_swap_b32_e32 v174, v175
	s_and_saveexec_b64 s[8:9], s[4:5]
	v_add_f32_e32 v174, v174, v175
	ds_write_b32 v200, v174 offset:512
	s_or_b64 exec, exec, s[8:9]
	v_and_b32_e32 v175, 0xffff0000, v172
	v_and_b32_e32 v177, 0xffff0000, v173
	v_lshlrev_b32_e32 v174, 16, v172
	v_lshlrev_b32_e32 v176, 16, v173
	v_pk_fma_f32 v[80:81], v[80:81], v[136:137], v[176:177]
	v_pk_fma_f32 v[78:79], v[78:79], v[134:135], v[174:175]
	v_and_b32_e32 v173, 0xffff0000, v170
	v_and_b32_e32 v179, 0xffff0000, v171
	v_lshlrev_b32_e32 v172, 16, v170
	v_lshlrev_b32_e32 v178, 16, v171
	v_and_b32_e32 v171, 0xffff0000, v168
	v_and_b32_e32 v181, 0xffff0000, v169
	v_lshlrev_b32_e32 v170, 16, v168
	v_lshlrev_b32_e32 v180, 16, v169
	v_and_b32_e32 v169, 0xffff0000, v166
	v_and_b32_e32 v183, 0xffff0000, v167
	v_lshlrev_b32_e32 v168, 16, v166
	v_lshlrev_b32_e32 v182, 16, v167
	v_mul_f32_e32 v166, v79, v79
	v_mul_f32_e32 v167, v81, v81
	v_fmac_f32_e32 v166, v78, v78
	v_fmac_f32_e32 v167, v80, v80
	v_pk_fma_f32 v[76:77], v[76:77], v[132:133], v[178:179]
	v_pk_fma_f32 v[74:75], v[74:75], v[130:131], v[172:173]
	v_add_f32_e32 v166, v166, v167
	v_mul_f32_e32 v167, v75, v75
	v_mul_f32_e32 v172, v77, v77
	v_fmac_f32_e32 v167, v74, v74
	v_fmac_f32_e32 v172, v76, v76
	v_add_f32_e32 v167, v167, v172
	v_pk_fma_f32 v[72:73], v[72:73], v[128:129], v[180:181]
	v_pk_fma_f32 v[70:71], v[70:71], v[126:127], v[170:171]
	v_add_f32_e32 v166, v166, v167
	v_mul_f32_e32 v167, v71, v71
	v_mul_f32_e32 v170, v73, v73
	v_fmac_f32_e32 v167, v70, v70
	v_fmac_f32_e32 v170, v72, v72
	v_add_f32_e32 v167, v167, v170
	v_pk_fma_f32 v[68:69], v[68:69], v[120:121], v[182:183]
	v_pk_fma_f32 v[66:67], v[66:67], v[118:119], v[168:169]
	v_add_f32_e32 v166, v166, v167
	v_mul_f32_e32 v167, v67, v67
	v_mul_f32_e32 v168, v69, v69
	v_fmac_f32_e32 v167, v66, v66
	v_fmac_f32_e32 v168, v68, v68
	v_add_f32_e32 v167, v167, v168
	v_add_f32_e32 v166, v166, v167
	v_mov_b32_e32 v167, v166
	s_nop 1
	v_permlane16_swap_b32_e32 v166, v167
	v_add_f32_e32 v166, v166, v167
	v_mov_b32_e32 v167, v166
	s_nop 1
	v_permlane32_swap_b32_e32 v166, v167
	s_and_saveexec_b64 s[8:9], s[4:5]
	v_add_f32_e32 v166, v166, v167
	ds_write_b32 v200, v166 offset:768
	s_or_b64 exec, exec, s[8:9]
	v_lshlrev_b64 v[162:163], 11, v[162:163]
	v_lshl_add_u64 v[162:163], v[164:165], 0, v[162:163]
	v_lshl_add_u64 v[162:163], v[162:163], 0, s[10:11]
	v_add_co_u32_e32 v168, vcc, 0x40000, v162
	v_lshl_add_u64 v[164:165], v[162:163], 0, s[38:39]
	s_nop 0
	v_addc_co_u32_e32 v169, vcc, 0, v163, vcc
	global_load_dwordx2 v[166:167], v[164:165], off offset:32
	global_load_dwordx2 v[170:171], v[164:165], off offset:256
	global_load_dwordx2 v[202:203], v[168:169], off
	global_load_dwordx2 v[204:205], v[164:165], off offset:288
	v_add_co_u32_e32 v168, vcc, s86, v162
	v_lshl_add_u64 v[164:165], v[162:163], 0, s[42:43]
	s_nop 0
	v_addc_co_u32_e32 v169, vcc, 0, v163, vcc
	v_add_co_u32_e32 v174, vcc, s87, v162
	v_lshl_add_u64 v[172:173], v[162:163], 0, s[44:45]
	s_nop 0
	v_addc_co_u32_e32 v175, vcc, 0, v163, vcc
	v_add_co_u32_e32 v176, vcc, s88, v162
	v_lshl_add_u64 v[206:207], v[162:163], 0, s[46:47]
	s_nop 0
	v_addc_co_u32_e32 v177, vcc, 0, v163, vcc
	global_load_dwordx2 v[188:189], v[168:169], off
	global_load_dwordx2 v[186:187], v[164:165], off offset:32
	global_load_dwordx2 v[184:185], v[164:165], off offset:256
	s_nop 0
	global_load_dwordx2 v[164:165], v[164:165], off offset:288
	s_nop 0
	global_load_dwordx2 v[182:183], v[174:175], off
	global_load_dwordx2 v[180:181], v[172:173], off offset:32
	global_load_dwordx2 v[168:169], v[172:173], off offset:256
	global_load_dwordx2 v[162:163], v[172:173], off offset:288
	global_load_dwordx2 v[178:179], v[176:177], off
	s_nop 0
	global_load_dwordx2 v[176:177], v[206:207], off offset:32
	global_load_dwordx2 v[174:175], v[206:207], off offset:256
	global_load_dwordx2 v[172:173], v[206:207], off offset:288
	s_waitcnt vmcnt(15)
	v_and_b32_e32 v207, 0xffff0000, v166
	v_lshlrev_b32_e32 v206, 16, v166
	v_and_b32_e32 v209, 0xffff0000, v167
	v_lshlrev_b32_e32 v208, 16, v167
	s_waitcnt vmcnt(14)
	v_and_b32_e32 v167, 0xffff0000, v170
	v_lshlrev_b32_e32 v166, 16, v170
	v_and_b32_e32 v211, 0xffff0000, v171
	v_lshlrev_b32_e32 v210, 16, v171
	s_waitcnt vmcnt(13)
	v_and_b32_e32 v171, 0xffff0000, v202
	v_lshlrev_b32_e32 v170, 16, v202
	v_and_b32_e32 v213, 0xffff0000, v203
	v_lshlrev_b32_e32 v212, 16, v203
	s_waitcnt vmcnt(12)
	v_and_b32_e32 v203, 0xffff0000, v204
	v_lshlrev_b32_e32 v202, 16, v204
	v_pk_fma_f32 v[64:65], v[64:65], v[132:133], v[208:209]
	v_pk_fma_f32 v[62:63], v[62:63], v[130:131], v[206:207]
	v_pk_fma_f32 v[56:57], v[56:57], v[128:129], v[210:211]
	v_pk_fma_f32 v[54:55], v[54:55], v[126:127], v[166:167]
	v_pk_fma_f32 v[166:167], v[60:61], v[136:137], v[212:213]
	v_pk_fma_f32 v[170:171], v[58:59], v[134:135], v[170:171]
	v_and_b32_e32 v215, 0xffff0000, v205
	v_lshlrev_b32_e32 v214, 16, v205
	v_mul_f32_e32 v58, v63, v63
	v_mul_f32_e32 v59, v65, v65
	v_mul_f32_e32 v60, v55, v55
	v_mul_f32_e32 v61, v57, v57
	v_pk_fma_f32 v[50:51], v[50:51], v[118:119], v[202:203]
	v_mul_f32_e32 v201, v171, v171
	v_mul_f32_e32 v202, v167, v167
	v_pk_fma_f32 v[52:53], v[52:53], v[120:121], v[214:215]
	v_fmac_f32_e32 v58, v62, v62
	v_fmac_f32_e32 v59, v64, v64
	v_fmac_f32_e32 v60, v54, v54
	v_fmac_f32_e32 v61, v56, v56
	v_fmac_f32_e32 v201, v170, v170
	v_fmac_f32_e32 v202, v166, v166
	v_mul_f32_e32 v203, v51, v51
	v_mul_f32_e32 v204, v53, v53
	v_add_f32_e32 v58, v58, v59
	v_add_f32_e32 v59, v60, v61
	v_add_f32_e32 v60, v201, v202
	v_fmac_f32_e32 v203, v50, v50
	v_fmac_f32_e32 v204, v52, v52
	v_add_f32_e32 v58, v60, v58
	v_add_f32_e32 v61, v203, v204
	v_add_f32_e32 v58, v58, v59
	v_add_f32_e32 v58, v58, v61
	v_mov_b32_e32 v59, v58
	s_nop 1
	v_permlane16_swap_b32_e32 v58, v59
	v_add_f32_e32 v58, v58, v59
	v_mov_b32_e32 v59, v58
	s_nop 1
	v_permlane32_swap_b32_e32 v58, v59
	s_and_saveexec_b64 s[8:9], s[4:5]
	v_add_f32_e32 v58, v58, v59
	ds_write_b32 v200, v58 offset:2048
	s_or_b64 exec, exec, s[8:9]
	s_waitcnt vmcnt(11)
	v_and_b32_e32 v59, 0xffff0000, v188
	v_and_b32_e32 v61, 0xffff0000, v189
	v_lshlrev_b32_e32 v58, 16, v188
	v_lshlrev_b32_e32 v60, 16, v189
	s_waitcnt vmcnt(10)
	v_and_b32_e32 v189, 0xffff0000, v186
	v_and_b32_e32 v203, 0xffff0000, v187
	v_lshlrev_b32_e32 v188, 16, v186
	v_lshlrev_b32_e32 v202, 16, v187
	s_waitcnt vmcnt(9)
	v_and_b32_e32 v187, 0xffff0000, v184
	v_and_b32_e32 v205, 0xffff0000, v185
	v_lshlrev_b32_e32 v186, 16, v184
	v_lshlrev_b32_e32 v204, 16, v185
	s_waitcnt vmcnt(8)
	v_and_b32_e32 v185, 0xffff0000, v164
	v_and_b32_e32 v207, 0xffff0000, v165
	v_lshlrev_b32_e32 v184, 16, v164
	v_lshlrev_b32_e32 v206, 16, v165
	v_pk_fma_f32 v[48:49], v[48:49], v[136:137], v[60:61]
	v_pk_fma_f32 v[60:61], v[44:45], v[132:133], v[202:203]
	v_pk_fma_f32 v[164:165], v[42:43], v[130:131], v[188:189]
	v_pk_fma_f32 v[58:59], v[46:47], v[134:135], v[58:59]
	v_mul_f32_e32 v42, v165, v165
	v_mul_f32_e32 v43, v61, v61
	v_mul_f32_e32 v46, v59, v59
	v_mul_f32_e32 v47, v49, v49
	v_fmac_f32_e32 v42, v164, v164
	v_fmac_f32_e32 v43, v60, v60
	v_pk_fma_f32 v[40:41], v[40:41], v[128:129], v[204:205]
	v_pk_fma_f32 v[38:39], v[38:39], v[126:127], v[186:187]
	v_fmac_f32_e32 v46, v58, v58
	v_fmac_f32_e32 v47, v48, v48
	v_add_f32_e32 v42, v42, v43
	v_mul_f32_e32 v43, v39, v39
	v_mul_f32_e32 v44, v41, v41
	v_add_f32_e32 v46, v46, v47
	v_fmac_f32_e32 v43, v38, v38
	v_fmac_f32_e32 v44, v40, v40
	v_add_f32_e32 v42, v46, v42
	v_add_f32_e32 v43, v43, v44
	v_pk_fma_f32 v[36:37], v[36:37], v[120:121], v[206:207]
	v_pk_fma_f32 v[34:35], v[34:35], v[118:119], v[184:185]
	v_add_f32_e32 v42, v42, v43
	v_mul_f32_e32 v43, v35, v35
	v_mul_f32_e32 v44, v37, v37
	v_fmac_f32_e32 v43, v34, v34
	v_fmac_f32_e32 v44, v36, v36
	v_add_f32_e32 v43, v43, v44
	v_add_f32_e32 v42, v42, v43
	v_mov_b32_e32 v43, v42
	s_nop 1
	v_permlane16_swap_b32_e32 v42, v43
	v_add_f32_e32 v42, v42, v43
	v_mov_b32_e32 v43, v42
	s_nop 1
	v_permlane32_swap_b32_e32 v42, v43
	s_and_saveexec_b64 s[8:9], s[4:5]
	v_add_f32_e32 v42, v42, v43
	ds_write_b32 v200, v42 offset:2304
	s_or_b64 exec, exec, s[8:9]
	s_waitcnt vmcnt(7)
	v_and_b32_e32 v43, 0xffff0000, v182
	v_and_b32_e32 v45, 0xffff0000, v183
	v_lshlrev_b32_e32 v42, 16, v182
	v_lshlrev_b32_e32 v44, 16, v183
	s_waitcnt vmcnt(6)
	v_and_b32_e32 v183, 0xffff0000, v180
	v_and_b32_e32 v185, 0xffff0000, v181
	v_lshlrev_b32_e32 v182, 16, v180
	v_lshlrev_b32_e32 v184, 16, v181
	s_waitcnt vmcnt(5)
	v_and_b32_e32 v181, 0xffff0000, v168
	v_and_b32_e32 v187, 0xffff0000, v169
	v_lshlrev_b32_e32 v180, 16, v168
	v_lshlrev_b32_e32 v186, 16, v169
	s_waitcnt vmcnt(4)
	v_and_b32_e32 v189, 0xffff0000, v162
	v_and_b32_e32 v203, 0xffff0000, v163
	v_lshlrev_b32_e32 v188, 16, v162
	v_lshlrev_b32_e32 v202, 16, v163
	v_pk_fma_f32 v[162:163], v[28:29], v[132:133], v[184:185]
	v_pk_fma_f32 v[168:169], v[26:27], v[130:131], v[182:183]
	v_mul_f32_e32 v27, v163, v163
	v_mul_f32_e32 v26, v169, v169
	v_fmac_f32_e32 v26, v168, v168
	v_fmac_f32_e32 v27, v162, v162
	v_pk_fma_f32 v[24:25], v[24:25], v[128:129], v[186:187]
	v_pk_fma_f32 v[22:23], v[22:23], v[126:127], v[180:181]
	v_pk_fma_f32 v[32:33], v[32:33], v[136:137], v[44:45]
	v_pk_fma_f32 v[46:47], v[30:31], v[134:135], v[42:43]
	v_add_f32_e32 v26, v26, v27
	v_mul_f32_e32 v27, v23, v23
	v_mul_f32_e32 v28, v25, v25
	v_mul_f32_e32 v30, v47, v47
	v_mul_f32_e32 v31, v33, v33
	v_fmac_f32_e32 v27, v22, v22
	v_fmac_f32_e32 v28, v24, v24
	v_fmac_f32_e32 v30, v46, v46
	v_fmac_f32_e32 v31, v32, v32
	v_add_f32_e32 v27, v27, v28
	v_pk_fma_f32 v[28:29], v[20:21], v[120:121], v[202:203]
	v_pk_fma_f32 v[44:45], v[18:19], v[118:119], v[188:189]
	v_add_f32_e32 v30, v30, v31
	v_mul_f32_e32 v18, v45, v45
	v_mul_f32_e32 v19, v29, v29
	v_add_f32_e32 v26, v30, v26
	v_fmac_f32_e32 v18, v44, v44
	v_fmac_f32_e32 v19, v28, v28
	v_add_f32_e32 v26, v26, v27
	v_add_f32_e32 v18, v18, v19
	v_add_f32_e32 v18, v26, v18
	v_mov_b32_e32 v19, v18
	s_nop 1
	v_permlane16_swap_b32_e32 v18, v19
	v_add_f32_e32 v18, v18, v19
	v_mov_b32_e32 v19, v18
	s_nop 1
	v_permlane32_swap_b32_e32 v18, v19
	s_and_saveexec_b64 s[8:9], s[4:5]
	v_add_f32_e32 v18, v18, v19
	ds_write_b32 v200, v18 offset:2560
	s_or_b64 exec, exec, s[8:9]
	s_waitcnt vmcnt(3)
	v_and_b32_e32 v19, 0xffff0000, v178
	v_and_b32_e32 v21, 0xffff0000, v179
	v_lshlrev_b32_e32 v18, 16, v178
	v_lshlrev_b32_e32 v20, 16, v179
	s_waitcnt vmcnt(2)
	v_and_b32_e32 v27, 0xffff0000, v176
	v_and_b32_e32 v31, 0xffff0000, v177
	v_lshlrev_b32_e32 v26, 16, v176
	v_lshlrev_b32_e32 v30, 16, v177
	s_waitcnt vmcnt(1)
	v_and_b32_e32 v177, 0xffff0000, v174
	v_and_b32_e32 v179, 0xffff0000, v175
	v_lshlrev_b32_e32 v176, 16, v174
	v_lshlrev_b32_e32 v178, 16, v175
	v_pk_fma_f32 v[42:43], v[16:17], v[136:137], v[20:21]
	v_pk_fma_f32 v[134:135], v[14:15], v[134:135], v[18:19]
	v_pk_fma_f32 v[132:133], v[12:13], v[132:133], v[30:31]
	v_pk_fma_f32 v[130:131], v[10:11], v[130:131], v[26:27]
	s_waitcnt vmcnt(0)
	v_and_b32_e32 v175, 0xffff0000, v172
	v_and_b32_e32 v181, 0xffff0000, v173
	v_lshlrev_b32_e32 v174, 16, v172
	v_lshlrev_b32_e32 v180, 16, v173
	v_mul_f32_e32 v14, v135, v135
	v_mul_f32_e32 v15, v43, v43
	v_mul_f32_e32 v10, v131, v131
	v_mul_f32_e32 v11, v133, v133
	v_pk_fma_f32 v[18:19], v[8:9], v[128:129], v[178:179]
	v_pk_fma_f32 v[20:21], v[6:7], v[126:127], v[176:177]
	v_fmac_f32_e32 v14, v134, v134
	v_fmac_f32_e32 v15, v42, v42
	v_fmac_f32_e32 v10, v130, v130
	v_fmac_f32_e32 v11, v132, v132
	v_mul_f32_e32 v6, v21, v21
	v_mul_f32_e32 v7, v19, v19
	v_pk_fma_f32 v[26:27], v[4:5], v[120:121], v[180:181]
	v_pk_fma_f32 v[30:31], v[2:3], v[118:119], v[174:175]
	v_add_f32_e32 v14, v14, v15
	v_add_f32_e32 v10, v10, v11
	v_fmac_f32_e32 v6, v20, v20
	v_fmac_f32_e32 v7, v18, v18
	v_mul_f32_e32 v2, v31, v31
	v_mul_f32_e32 v3, v27, v27
	v_add_f32_e32 v10, v14, v10
	v_add_f32_e32 v6, v6, v7
	v_fmac_f32_e32 v2, v30, v30
	v_fmac_f32_e32 v3, v26, v26
	v_add_f32_e32 v6, v10, v6
	v_add_f32_e32 v2, v2, v3
	v_add_f32_e32 v2, v6, v2
	v_mov_b32_e32 v3, v2
	s_nop 1
	v_permlane16_swap_b32_e32 v2, v3
	v_add_f32_e32 v2, v2, v3
	v_mov_b32_e32 v3, v2
	s_nop 1
	v_permlane32_swap_b32_e32 v2, v3
	s_and_saveexec_b64 s[8:9], s[4:5]
	v_add_f32_e32 v2, v2, v3
	ds_write_b32 v200, v2 offset:2816
	s_or_b64 exec, exec, s[8:9]
	s_ashr_i32 s4, s57, 1
	v_mov_b32_e32 v2, s4
	s_waitcnt lgkmcnt(0)
	s_barrier
	v_bfi_b32 v4, s83, v2, v161
	v_and_b32_e32 v5, 63, v161
	v_add_u32_e32 v2, s7, v4
	v_cmp_gt_u32_e64 s[8:9], 32, v5
	v_ashrrev_i32_e32 v3, 31, v2
	s_and_saveexec_b64 s[4:5], s[8:9]
	s_cbranch_execz .LBB0_876
	v_lshl_add_u32 v6, v4, 4, 0
	v_add_u32_e32 v6, 0x20000, v6
	ds_read_b128 v[6:9], v6
	v_lshl_add_u64 v[10:11], v[2:3], 4, s[16:17]
	s_ashr_i32 s7, s6, 31
	v_lshl_add_u64 v[10:11], s[6:7], 2, v[10:11]
	s_waitcnt lgkmcnt(0)
	v_mov_b32_e32 v12, v7
	v_mov_b32_e32 v13, v8
	v_mov_b32_e32 v7, v9
	v_pk_add_f32 v[6:7], v[12:13], v[6:7]
	s_nop 0
	v_pk_add_f32 v[6:7], v[6:7], v[6:7] op_sel:[0,1] op_sel_hi:[1,0]
	global_store_dword v[10:11], v6, off sc1
